# NSA compressed-branch bias/mask: 16 batched sentinel-table reads + in-place adds per sub-tile instead of 16 serialized exec-masked LDS round trips
# baseline (speedup 1.0000x reference)
; #define LAS __attribute__((address_space(3)))
; DI int opaque_tid(int wv) { unsigned ones = ~0u; asm volatile("" : "+s"(ones)); int t = wv * 64 + (int)__builtin_amdgcn_mbcnt_hi(ones, __builtin_amdgcn_mbcnt_lo(ones, 0u)); asm volatile("" : "+v"(t)); return t; }
; DI void nsa_attn_phase(int wv, LAS unsigned char* lds, const bf16_t* Q, const bf16_t* slab, const bf16_t* VT2, const float* gates, const bf16_t* KCMP, const bf16_t* VCMPT,
;                        const float* rel_bias, bf16_t* O) {
;     ...
;         const int b = item >> 4, g = (item >> 2) & 3, qtr = item & 3;
;         const int head = g * 4 + rhead;
;         const size_t bg = (size_t)(b * 4 + g);
;         int tid = opaque_tid(wv), lane = tid & 63;
;         __syncthreads();
; #pragma unroll
;         for (int e = 0; e < 2; ++e) { const int pc = tid + 512 * e;
;             const u32x4 v = *(const u32x4*)(KCMP + bg * 128 * 64 + (size_t)pc * 8); *(LAS u32x4*)(lds + OFF_KC + (pc >> 3) * KCS + (pc & 7) * 16) = v;
;             const u32x4 v2 = *(const u32x4*)(VCMPT + bg * 64 * 128 + (size_t)pc * 8); lds_store16_as2x8(lds + OFF_VC + (pc >> 4) * VCS + (pc & 15) * 16, v2); }
;         lut[tid] = rel_bias[t5_bucket(tid & 127) * 16 + g * 4 + (tid >> 7)] * LOG2E;
;         __syncthreads();
;         const LAS float* mylut = lut + rhead * 128;
.LBB0_2238:
	s_or_b64 exec, exec, s[6:7]
	s_lshl_b32 s6, s0, 2
	v_lshlrev_b32_e32 v0, 4, v0
	v_ashrrev_i32_e32 v3, 7, v2
	v_add3_u32 v4, s6, v3, v0
	v_readlane_b32 s16, v254, 2
	v_ashrrev_i32_e32 v5, 31, v4
	v_readlane_b32 s22, v254, 8
	v_readlane_b32 s23, v254, 9
	v_readlane_b32 s17, v254, 3
	s_and_b32 s66, s1, 3
	v_lshl_add_u64 v[4:5], v[4:5], 2, s[22:23]
	global_load_dword v0, v[4:5], off
	s_ashr_i32 s3, s2, 31
	s_or_b32 s1, s6, s56
	v_readlane_b32 s18, v254, 4
	s_xor_b32 s67, s66, 3
	s_lshl_b64 s[16:17], s[2:3], 11
	s_lshl_b32 s6, s1, 7
	v_readlane_b32 s19, v254, 5
	s_add_u32 s18, s38, s6
	v_readlane_b32 s20, v254, 6
	s_mul_i32 s1, s1, 12
	s_addc_u32 s19, s39, 0
	v_readlane_b32 s21, v254, 7
	s_add_u32 s20, s48, s1
	s_addc_u32 s21, s49, 0
	s_lshl_b64 s[4:5], s[4:5], 18
	s_add_u32 s69, s46, s4
	s_addc_u32 s84, s47, s5
	s_lshl_b64 s[22:23], s[2:3], 9
	s_lshl_b32 s0, s0, 6
	v_readlane_b32 s24, v254, 10
	s_or_b32 s22, s22, s0
	v_readlane_b32 s25, v254, 11
	v_lshl_add_u32 v2, v2, 2, 0
	s_add_u32 s24, s44, s6
	v_add_u32_e32 v2, 0x1a300, v2
	s_addc_u32 s25, s45, 0
	s_mov_b32 s85, 0
	v_readlane_b32 s26, v254, 12
	v_readlane_b32 s27, v254, 13
	v_readlane_b32 s28, v254, 14
	v_readlane_b32 s29, v254, 15
	v_readlane_b32 s30, v254, 16
	v_readlane_b32 s31, v254, 17
	s_waitcnt vmcnt(0)
	v_mul_f32_e32 v0, 0x3fb8aa3b, v0
	ds_write_b32 v2, v0
	s_waitcnt lgkmcnt(0)
	s_barrier
	s_mov_b32 s0, -1
	v_mbcnt_lo_u32_b32 v0, s0, 0
	v_mbcnt_hi_u32_b32 v0, s0, v0
	v_add_u32_e32 v2, s11, v0
	v_subrev_u32_e32 v3, 64, v2
	v_mov_b32_e32 v5, 0x7f
	v_med3_i32 v4, v3, 0, v5
	v_lshlrev_b32_e32 v4, 2, v4
	v_lshlrev_b32_e32 v6, 2, v2
	v_mov_b32_e32 v9, 0xf149f2ca
	v_add_u32_e32 v7, 0x1a300, v4
	ds_read_b32 v10, v7
	v_add_u32_e32 v7, 0x1a500, v4
	ds_read_b32 v11, v7
	v_add_u32_e32 v7, 0x1a700, v4
	ds_read_b32 v12, v7
	v_add_u32_e32 v7, 0x1a900, v4
	ds_read_b32 v13, v7
	v_cmp_gt_i32_e32 vcc, 0, v3
	s_waitcnt lgkmcnt(0)
	v_cndmask_b32_e32 v10, v10, v9, vcc
	v_add_u32_e32 v7, 0x1ab00, v6
	ds_write_b32 v7, v10
	v_cndmask_b32_e32 v11, v11, v9, vcc
	v_add_u32_e32 v7, 0x1b600, v6
	ds_write_b32 v7, v11
	v_cndmask_b32_e32 v12, v12, v9, vcc
	v_add_u32_e32 v7, 0x1c100, v6
	ds_write_b32 v7, v12
	v_cndmask_b32_e32 v13, v13, v9, vcc
	v_add_u32_e32 v7, 0x1cc00, v6
	ds_write_b32 v7, v13
	v_cmp_gt_u32_e32 vcc, 0xc0, v2
	s_and_saveexec_b64 s[0:1], vcc
	v_mov_b32_e32 v7, 0x1a4fc
	ds_read_b32 v10, v7
	v_mov_b32_e32 v7, 0x1a6fc
	ds_read_b32 v11, v7
	v_mov_b32_e32 v7, 0x1a8fc
	ds_read_b32 v12, v7
	v_mov_b32_e32 v7, 0x1aafc
	ds_read_b32 v13, v7
	v_cmp_gt_u32_e32 vcc, 64, v2
	s_waitcnt lgkmcnt(0)
	v_cndmask_b32_e32 v10, v9, v10, vcc
	v_add_u32_e32 v7, 0x1b300, v6
	ds_write_b32 v7, v10
	v_cndmask_b32_e32 v11, v9, v11, vcc
	v_add_u32_e32 v7, 0x1be00, v6
	ds_write_b32 v7, v11
	v_cndmask_b32_e32 v12, v9, v12, vcc
	v_add_u32_e32 v7, 0x1c900, v6
	ds_write_b32 v7, v12
	v_cndmask_b32_e32 v13, v9, v13, vcc
	v_add_u32_e32 v7, 0x1d400, v6
	ds_write_b32 v7, v13
	s_or_b64 exec, exec, s[0:1]
	s_sub_i32 s70, s57, 0x1a300
	s_mul_i32 s70, s70, 11
	s_lshr_b32 s70, s70, 1
	s_add_i32 s70, s70, 0x1aa14
	s_add_i32 s71, s70, 0x1ec
	s_waitcnt lgkmcnt(0)
	s_barrier
	s_branch .LBB0_2240

; #define LAS __attribute__((address_space(3)))
; DI f32x16 mfma32(bf16x8 a, bf16x8 b, f32x16 c) { return __builtin_amdgcn_mfma_f32_32x32x16_bf16(a, b, c, 0, 0, 0); }
; DI void nsa_attn_phase(int wv, LAS unsigned char* lds, const bf16_t* Q, const bf16_t* slab, const bf16_t* VT2, const float* gates, const bf16_t* KCMP, const bf16_t* VCMPT,
;                        const float* rel_bias, bf16_t* O) {
;     ...
;         for (int qi = 0; qi < 8; ++qi) {
;             tid = opaque_tid(wv); lane = tid & 63; const int r = lane & 31, hh = lane >> 5;
;             const int qblk = 4 * qi + ((qi & 1) ? 3 - qtr : qtr), T0 = 64 * qblk, TW = T0 + 32 * half;
;             const int tq = TW + r; const size_t token = (size_t)b * SEQ + tq;
;             const float c31 = mylut[127];
;             bf16x8 qf[4];
; #pragma unroll
;             for (int ks = 0; ks < 4; ++ks) qf[ks] = *(const bf16x8*)(Q + token * 1024 + head * 64 + 16 * ks + 8 * hh);
;             const float g0 = gates[token * 48 + head * 3], g1 = gates[token * 48 + head * 3 + 1], g2 = gates[token * 48 + head * 3 + 2];
;             f32x16 out[2] = {zero16(), zero16()};
;             const bool need_rank = qblk >= 16;
;             {
;                 const int nsub = (TW >> 9) + 1;
;                 f32x16 s4[4];
;                 float mx = NEGF;
; #pragma unroll
;                 for (int t = 0; t < 4; ++t) {
;                     if (t < nsub) {
;                         const bool farc = TW - (16 * (32 * t + 31) + 31) >= 127;
;                         s4[t] = splat16(farc ? c31 : 0.f);
;                         bf16x8 kfc[4];
; #pragma unroll
;                         for (int ks = 0; ks < 4; ++ks) kfc[ks] = *(const LAS bf16x8*)(lds + OFF_KC + (32 * t + r) * KCS + 32 * ks + 16 * hh);
; #pragma unroll
;                         for (int ks = 0; ks < 4; ++ks) s4[t] = mfma32(kfc[ks], qf[ks], s4[t]);
;                         if (!farc) {
;                             const int d0 = tq - 31 - 16 * (32 * t + 4 * hh);
; #pragma unroll
;                             for (int i = 0; i < 16; ++i) {
;                                 const int dist = d0 - 16 * ((i & 3) + 8 * (i >> 2));
;                                 const float bias = mylut[dist < 0 ? 0 : (dist > 127 ? 127 : dist)];
;                                 s4[t][i] = dist >= 0 ? s4[t][i] + bias : NEGF;
;                             }
;                         }
.LBB0_2240:
	s_mov_b32 s0, -1
	v_mov_b32_e32 v213, v1
	v_mbcnt_lo_u32_b32 v0, s0, 0
	v_mbcnt_hi_u32_b32 v0, s0, v0
	s_lshl_b32 s0, s85, 2
	s_bitcmp0_b32 s85, 0
	s_cselect_b32 s1, s66, s67
	s_or_b32 s26, s1, s0
	v_add_u32_e32 v114, s11, v0
	s_lshl_b32 s90, s26, 6
	s_add_i32 s90, s90, s60
	v_and_b32_e32 v112, 31, v114
	v_or_b32_e32 v210, s90, v112
	v_ashrrev_i32_e32 v211, 31, v210
	v_lshl_add_u64 v[2:3], s[16:17], 0, v[210:211]
	v_bfe_u32 v97, v114, 5, 1
	v_lshlrev_b64 v[4:5], 11, v[2:3]
	v_lshl_add_u64 v[4:5], s[18:19], 0, v[4:5]
	v_lshlrev_b32_e32 v212, 4, v97
	v_lshl_add_u64 v[4:5], v[4:5], 0, v[212:213]
	flat_load_dwordx4 v[176:179], v[4:5]
	flat_load_dwordx4 v[180:183], v[4:5] offset:32
	flat_load_dwordx4 v[184:187], v[4:5] offset:64
	flat_load_dwordx4 v[188:191], v[4:5] offset:96
	v_mov_b64_e32 v[4:5], s[20:21]
	v_mad_u64_u32 v[4:5], s[0:1], v2, s41, v[4:5]
	v_mad_i32_i24 v5, v3, s41, v5
	flat_load_dwordx3 v[204:206], v[4:5]
	v_mov_b32_e32 v0, s57
	ds_read_b32 v113, v0 offset:508
	s_ashr_i32 s0, s90, 9
	v_add_u32_e32 v96, 0, v212
	s_cmp_gt_i32 s0, -1
	v_mul_i32_i24_e32 v0, 0xffffffc0, v97
	v_mov_b32_e32 v98, 0xf149f2ca
	s_cselect_b64 s[4:5], -1, 0
	s_cmp_lt_i32 s0, 0
	v_mad_u32_u24 v2, v112, s87, v96
	s_cbranch_scc1 .LBB0_2276
	ds_read_b128 v[4:7], v2
	s_cmpk_gt_u32 s90, 0x28d
	s_cselect_b64 vcc, -1, 0
	s_waitcnt lgkmcnt(0)
	v_cndmask_b32_e32 v64, 0, v113, vcc
	v_mov_b32_e32 v65, v64
	v_mov_b32_e32 v66, v64
	v_mov_b32_e32 v67, v64
	v_mov_b32_e32 v68, v64
	v_mov_b32_e32 v69, v64
	v_mov_b32_e32 v70, v64
	v_mov_b32_e32 v71, v64
	v_mov_b32_e32 v72, v64
	v_mov_b32_e32 v73, v64
	v_mov_b32_e32 v74, v64
	v_mov_b32_e32 v75, v64
	v_mov_b32_e32 v76, v64
	v_mov_b32_e32 v77, v64
	v_mov_b32_e32 v78, v64
	v_mov_b32_e32 v79, v64
	s_and_b64 vcc, exec, vcc
	s_waitcnt vmcnt(0)
	v_mfma_f32_32x32x16_bf16 v[64:79], v[4:7], v[176:179], v[64:79]
	ds_read_b128 v[4:7], v2 offset:32
	s_waitcnt lgkmcnt(0)
	v_mfma_f32_32x32x16_bf16 v[64:79], v[4:7], v[180:183], v[64:79]
	ds_read_b128 v[4:7], v2 offset:64
	s_waitcnt lgkmcnt(0)
	v_mfma_f32_32x32x16_bf16 v[64:79], v[4:7], v[184:187], v[64:79]
	ds_read_b128 v[4:7], v2 offset:96
	s_waitcnt lgkmcnt(0)
	v_mfma_f32_32x32x16_bf16 v[64:79], v[4:7], v[188:191], v[64:79]
	s_cbranch_vccnz .LBB0_2275
	s_movk_i32 s1, 0xffe1
	v_add3_u32 v3, v210, v0, s1
	v_mov_b32_e32 v4, 0xffffffc0
	v_mov_b32_e32 v5, 0x1ff
	v_med3_i32 v80, v3, v4, v5
	v_lshl_add_u32 v80, v80, 2, s71
	ds_read_b32 v80, v80
	v_add_u32_e32 v81, 0xfffffff0, v3
	v_med3_i32 v81, v81, v4, v5
	v_lshl_add_u32 v81, v81, 2, s71
	ds_read_b32 v81, v81
	v_add_u32_e32 v82, 0xffffffe0, v3
	v_med3_i32 v82, v82, v4, v5
	v_lshl_add_u32 v82, v82, 2, s71
	ds_read_b32 v82, v82
	v_add_u32_e32 v83, 0xffffffd0, v3
	v_med3_i32 v83, v83, v4, v5
	v_lshl_add_u32 v83, v83, 2, s71
	ds_read_b32 v83, v83
	v_add_u32_e32 v84, 0xffffff80, v3
	v_med3_i32 v84, v84, v4, v5
	v_lshl_add_u32 v84, v84, 2, s71
	ds_read_b32 v84, v84
	v_add_u32_e32 v85, 0xffffff70, v3
	v_med3_i32 v85, v85, v4, v5
	v_lshl_add_u32 v85, v85, 2, s71
	ds_read_b32 v85, v85
	v_add_u32_e32 v86, 0xffffff60, v3
	v_med3_i32 v86, v86, v4, v5
	v_lshl_add_u32 v86, v86, 2, s71
	ds_read_b32 v86, v86
	v_add_u32_e32 v87, 0xffffff50, v3
	v_med3_i32 v87, v87, v4, v5
	v_lshl_add_u32 v87, v87, 2, s71
	ds_read_b32 v87, v87
	v_add_u32_e32 v88, 0xffffff00, v3
	v_med3_i32 v88, v88, v4, v5
	v_lshl_add_u32 v88, v88, 2, s71
	ds_read_b32 v88, v88
	v_add_u32_e32 v89, 0xfffffef0, v3
	v_med3_i32 v89, v89, v4, v5
	v_lshl_add_u32 v89, v89, 2, s71
	ds_read_b32 v89, v89
	v_add_u32_e32 v90, 0xfffffee0, v3
	v_med3_i32 v90, v90, v4, v5
	v_lshl_add_u32 v90, v90, 2, s71
	ds_read_b32 v90, v90
	v_add_u32_e32 v91, 0xfffffed0, v3
	v_med3_i32 v91, v91, v4, v5
	v_lshl_add_u32 v91, v91, 2, s71
	ds_read_b32 v91, v91
	v_add_u32_e32 v92, 0xfffffe80, v3
	v_med3_i32 v92, v92, v4, v5
	v_lshl_add_u32 v92, v92, 2, s71
	ds_read_b32 v92, v92
	v_add_u32_e32 v93, 0xfffffe70, v3
	v_med3_i32 v93, v93, v4, v5
	v_lshl_add_u32 v93, v93, 2, s71
	ds_read_b32 v93, v93
	v_add_u32_e32 v94, 0xfffffe60, v3
	v_med3_i32 v94, v94, v4, v5
	v_lshl_add_u32 v94, v94, 2, s71
	ds_read_b32 v94, v94
	v_add_u32_e32 v95, 0xfffffe50, v3
	v_med3_i32 v95, v95, v4, v5
	v_lshl_add_u32 v95, v95, 2, s71
	ds_read_b32 v95, v95
	s_waitcnt lgkmcnt(15)
	v_add_f32_e32 v64, v64, v80
	s_waitcnt lgkmcnt(14)
	v_add_f32_e32 v65, v65, v81
	s_waitcnt lgkmcnt(13)
	v_add_f32_e32 v66, v66, v82
	s_waitcnt lgkmcnt(12)
	v_add_f32_e32 v67, v67, v83
	s_waitcnt lgkmcnt(11)
	v_add_f32_e32 v68, v68, v84
	s_waitcnt lgkmcnt(10)
	v_add_f32_e32 v69, v69, v85
	s_waitcnt lgkmcnt(9)
	v_add_f32_e32 v70, v70, v86
	s_waitcnt lgkmcnt(8)
	v_add_f32_e32 v71, v71, v87
	s_waitcnt lgkmcnt(7)
	v_add_f32_e32 v72, v72, v88
	s_waitcnt lgkmcnt(6)
	v_add_f32_e32 v73, v73, v89
	s_waitcnt lgkmcnt(5)
	v_add_f32_e32 v74, v74, v90
	s_waitcnt lgkmcnt(4)
	v_add_f32_e32 v75, v75, v91
	s_waitcnt lgkmcnt(3)
	v_add_f32_e32 v76, v76, v92
	s_waitcnt lgkmcnt(2)
	v_add_f32_e32 v77, v77, v93
	s_waitcnt lgkmcnt(1)
	v_add_f32_e32 v78, v78, v94
	s_waitcnt lgkmcnt(0)
	v_add_f32_e32 v79, v79, v95

; #define LAS __attribute__((address_space(3)))
; DI f32x16 mfma32(bf16x8 a, bf16x8 b, f32x16 c) { return __builtin_amdgcn_mfma_f32_32x32x16_bf16(a, b, c, 0, 0, 0); }
; DI f32x16 splat16(float v) { f32x16 z; for (int i = 0; i < 16; ++i) z[i] = v; return z; }
; DI void nsa_attn_phase(int wv, LAS unsigned char* lds, const bf16_t* Q, const bf16_t* slab, const bf16_t* VT2, const float* gates, const bf16_t* KCMP, const bf16_t* VCMPT,
;                        const float* rel_bias, bf16_t* O) {
;     ...
;                 for (int t = 0; t < 4; ++t) {
;                     if (t < nsub) {
;                         const bool farc = TW - (16 * (32 * t + 31) + 31) >= 127;
;                         s4[t] = splat16(farc ? c31 : 0.f);
;                         bf16x8 kfc[4];
; #pragma unroll
;                         for (int ks = 0; ks < 4; ++ks) kfc[ks] = *(const LAS bf16x8*)(lds + OFF_KC + (32 * t + r) * KCS + 32 * ks + 16 * hh);
; #pragma unroll
;                         for (int ks = 0; ks < 4; ++ks) s4[t] = mfma32(kfc[ks], qf[ks], s4[t]);
;                         if (!farc) {
;                             const int d0 = tq - 31 - 16 * (32 * t + 4 * hh);
; #pragma unroll
;                             for (int i = 0; i < 16; ++i) {
;                                 const int dist = d0 - 16 * ((i & 3) + 8 * (i >> 2));
;                                 const float bias = mylut[dist < 0 ? 0 : (dist > 127 ? 127 : dist)];
;                                 s4[t][i] = dist >= 0 ? s4[t][i] + bias : NEGF;
;                             }
;                         }
; #pragma unroll
;                         for (int i = 0; i < 16; ++i) mx = fmaxf(mx, s4[t][i]);
;                     }
.LBB0_2276:
	v_and_b32_e32 v118, 63, v114
	v_lshlrev_b32_e32 v211, 3, v97
	s_cmp_gt_i32 s0, 0
	s_cselect_b64 s[6:7], -1, 0
	s_cmp_lt_i32 s0, 1
	s_cbranch_scc1 .LBB0_2312
	ds_read_b128 v[4:7], v2 offset:4608
	s_cmpk_gt_u32 s90, 0x48d
	s_cselect_b64 vcc, -1, 0
	s_waitcnt lgkmcnt(0)
	v_cndmask_b32_e32 v48, 0, v113, vcc
	v_mov_b32_e32 v49, v48
	v_mov_b32_e32 v50, v48
	v_mov_b32_e32 v51, v48
	v_mov_b32_e32 v52, v48
	v_mov_b32_e32 v53, v48
	v_mov_b32_e32 v54, v48
	v_mov_b32_e32 v55, v48
	v_mov_b32_e32 v56, v48
	v_mov_b32_e32 v57, v48
	v_mov_b32_e32 v58, v48
	v_mov_b32_e32 v59, v48
	v_mov_b32_e32 v60, v48
	v_mov_b32_e32 v61, v48
	v_mov_b32_e32 v62, v48
	v_mov_b32_e32 v63, v48
	s_and_b64 vcc, exec, vcc
	s_waitcnt vmcnt(0)
	v_mfma_f32_32x32x16_bf16 v[48:63], v[4:7], v[176:179], v[48:63]
	ds_read_b128 v[4:7], v2 offset:4640
	s_waitcnt lgkmcnt(0)
	v_mfma_f32_32x32x16_bf16 v[48:63], v[4:7], v[180:183], v[48:63]
	ds_read_b128 v[4:7], v2 offset:4672
	s_waitcnt lgkmcnt(0)
	v_mfma_f32_32x32x16_bf16 v[48:63], v[4:7], v[184:187], v[48:63]
	ds_read_b128 v[4:7], v2 offset:4704
	s_waitcnt lgkmcnt(0)
	v_mfma_f32_32x32x16_bf16 v[48:63], v[4:7], v[188:191], v[48:63]
	s_cbranch_vccnz .LBB0_2311
	s_movk_i32 s1, 0xfde1
	v_add3_u32 v3, v210, v0, s1
	v_mov_b32_e32 v4, 0xffffffc0
	v_mov_b32_e32 v5, 0x1ff
	v_med3_i32 v80, v3, v4, v5
	v_lshl_add_u32 v80, v80, 2, s71
	ds_read_b32 v80, v80
	v_add_u32_e32 v81, 0xfffffff0, v3
	v_med3_i32 v81, v81, v4, v5
	v_lshl_add_u32 v81, v81, 2, s71
	ds_read_b32 v81, v81
	v_add_u32_e32 v82, 0xffffffe0, v3
	v_med3_i32 v82, v82, v4, v5
	v_lshl_add_u32 v82, v82, 2, s71
	ds_read_b32 v82, v82
	v_add_u32_e32 v83, 0xffffffd0, v3
	v_med3_i32 v83, v83, v4, v5
	v_lshl_add_u32 v83, v83, 2, s71
	ds_read_b32 v83, v83
	v_add_u32_e32 v84, 0xffffff80, v3
	v_med3_i32 v84, v84, v4, v5
	v_lshl_add_u32 v84, v84, 2, s71
	ds_read_b32 v84, v84
	v_add_u32_e32 v85, 0xffffff70, v3
	v_med3_i32 v85, v85, v4, v5
	v_lshl_add_u32 v85, v85, 2, s71
	ds_read_b32 v85, v85
	v_add_u32_e32 v86, 0xffffff60, v3
	v_med3_i32 v86, v86, v4, v5
	v_lshl_add_u32 v86, v86, 2, s71
	ds_read_b32 v86, v86
	v_add_u32_e32 v87, 0xffffff50, v3
	v_med3_i32 v87, v87, v4, v5
	v_lshl_add_u32 v87, v87, 2, s71
	ds_read_b32 v87, v87
	v_add_u32_e32 v88, 0xffffff00, v3
	v_med3_i32 v88, v88, v4, v5
	v_lshl_add_u32 v88, v88, 2, s71
	ds_read_b32 v88, v88
	v_add_u32_e32 v89, 0xfffffef0, v3
	v_med3_i32 v89, v89, v4, v5
	v_lshl_add_u32 v89, v89, 2, s71
	ds_read_b32 v89, v89
	v_add_u32_e32 v90, 0xfffffee0, v3
	v_med3_i32 v90, v90, v4, v5
	v_lshl_add_u32 v90, v90, 2, s71
	ds_read_b32 v90, v90
	v_add_u32_e32 v91, 0xfffffed0, v3
	v_med3_i32 v91, v91, v4, v5
	v_lshl_add_u32 v91, v91, 2, s71
	ds_read_b32 v91, v91
	v_add_u32_e32 v92, 0xfffffe80, v3
	v_med3_i32 v92, v92, v4, v5
	v_lshl_add_u32 v92, v92, 2, s71
	ds_read_b32 v92, v92
	v_add_u32_e32 v93, 0xfffffe70, v3
	v_med3_i32 v93, v93, v4, v5
	v_lshl_add_u32 v93, v93, 2, s71
	ds_read_b32 v93, v93
	v_add_u32_e32 v94, 0xfffffe60, v3
	v_med3_i32 v94, v94, v4, v5
	v_lshl_add_u32 v94, v94, 2, s71
	ds_read_b32 v94, v94
	v_add_u32_e32 v95, 0xfffffe50, v3
	v_med3_i32 v95, v95, v4, v5
	v_lshl_add_u32 v95, v95, 2, s71
	ds_read_b32 v95, v95
	s_waitcnt lgkmcnt(15)
	v_add_f32_e32 v48, v48, v80
	s_waitcnt lgkmcnt(14)
	v_add_f32_e32 v49, v49, v81
	s_waitcnt lgkmcnt(13)
	v_add_f32_e32 v50, v50, v82
	s_waitcnt lgkmcnt(12)
	v_add_f32_e32 v51, v51, v83
	s_waitcnt lgkmcnt(11)
	v_add_f32_e32 v52, v52, v84
	s_waitcnt lgkmcnt(10)
	v_add_f32_e32 v53, v53, v85
	s_waitcnt lgkmcnt(9)
	v_add_f32_e32 v54, v54, v86
	s_waitcnt lgkmcnt(8)
	v_add_f32_e32 v55, v55, v87
	s_waitcnt lgkmcnt(7)
	v_add_f32_e32 v56, v56, v88
	s_waitcnt lgkmcnt(6)
	v_add_f32_e32 v57, v57, v89
	s_waitcnt lgkmcnt(5)
	v_add_f32_e32 v58, v58, v90
	s_waitcnt lgkmcnt(4)
	v_add_f32_e32 v59, v59, v91
	s_waitcnt lgkmcnt(3)
	v_add_f32_e32 v60, v60, v92
	s_waitcnt lgkmcnt(2)
	v_add_f32_e32 v61, v61, v93
	s_waitcnt lgkmcnt(1)
	v_add_f32_e32 v62, v62, v94
	s_waitcnt lgkmcnt(0)
	v_add_f32_e32 v63, v63, v95

; #define LAS __attribute__((address_space(3)))
; DI f32x16 mfma32(bf16x8 a, bf16x8 b, f32x16 c) { return __builtin_amdgcn_mfma_f32_32x32x16_bf16(a, b, c, 0, 0, 0); }
; DI f32x16 splat16(float v) { f32x16 z; for (int i = 0; i < 16; ++i) z[i] = v; return z; }
; DI void nsa_attn_phase(int wv, LAS unsigned char* lds, const bf16_t* Q, const bf16_t* slab, const bf16_t* VT2, const float* gates, const bf16_t* KCMP, const bf16_t* VCMPT,
;                        const float* rel_bias, bf16_t* O) {
;     ...
;                 for (int t = 0; t < 4; ++t) {
;                     if (t < nsub) {
;                         const bool farc = TW - (16 * (32 * t + 31) + 31) >= 127;
;                         s4[t] = splat16(farc ? c31 : 0.f);
;                         bf16x8 kfc[4];
; #pragma unroll
;                         for (int ks = 0; ks < 4; ++ks) kfc[ks] = *(const LAS bf16x8*)(lds + OFF_KC + (32 * t + r) * KCS + 32 * ks + 16 * hh);
; #pragma unroll
;                         for (int ks = 0; ks < 4; ++ks) s4[t] = mfma32(kfc[ks], qf[ks], s4[t]);
;                         if (!farc) {
;                             const int d0 = tq - 31 - 16 * (32 * t + 4 * hh);
; #pragma unroll
;                             for (int i = 0; i < 16; ++i) {
;                                 const int dist = d0 - 16 * ((i & 3) + 8 * (i >> 2));
;                                 const float bias = mylut[dist < 0 ? 0 : (dist > 127 ? 127 : dist)];
;                                 s4[t][i] = dist >= 0 ? s4[t][i] + bias : NEGF;
;                             }
;                         }
; #pragma unroll
;                         for (int i = 0; i < 16; ++i) mx = fmaxf(mx, s4[t][i]);
;                     }
.LBB0_2312:
	s_cmp_gt_i32 s0, 1
	s_cselect_b64 s[8:9], -1, 0
	s_cmp_lt_i32 s0, 2
	s_cbranch_scc1 .LBB0_2348
	ds_read_b128 v[4:7], v2 offset:9216
	s_cmpk_gt_u32 s90, 0x68d
	s_cselect_b64 vcc, -1, 0
	s_waitcnt lgkmcnt(0)
	v_cndmask_b32_e32 v32, 0, v113, vcc
	v_mov_b32_e32 v33, v32
	v_mov_b32_e32 v34, v32
	v_mov_b32_e32 v35, v32
	v_mov_b32_e32 v36, v32
	v_mov_b32_e32 v37, v32
	v_mov_b32_e32 v38, v32
	v_mov_b32_e32 v39, v32
	v_mov_b32_e32 v40, v32
	v_mov_b32_e32 v41, v32
	v_mov_b32_e32 v42, v32
	v_mov_b32_e32 v43, v32
	v_mov_b32_e32 v44, v32
	v_mov_b32_e32 v45, v32
	v_mov_b32_e32 v46, v32
	v_mov_b32_e32 v47, v32
	s_and_b64 vcc, exec, vcc
	s_waitcnt vmcnt(0)
	v_mfma_f32_32x32x16_bf16 v[32:47], v[4:7], v[176:179], v[32:47]
	ds_read_b128 v[4:7], v2 offset:9248
	s_waitcnt lgkmcnt(0)
	v_mfma_f32_32x32x16_bf16 v[32:47], v[4:7], v[180:183], v[32:47]
	ds_read_b128 v[4:7], v2 offset:9280
	s_waitcnt lgkmcnt(0)
	v_mfma_f32_32x32x16_bf16 v[32:47], v[4:7], v[184:187], v[32:47]
	ds_read_b128 v[4:7], v2 offset:9312
	s_waitcnt lgkmcnt(0)
	v_mfma_f32_32x32x16_bf16 v[32:47], v[4:7], v[188:191], v[32:47]
	s_cbranch_vccnz .LBB0_2347
	s_movk_i32 s1, 0xfbe1
	v_add3_u32 v3, v210, v0, s1
	v_mov_b32_e32 v4, 0xffffffc0
	v_mov_b32_e32 v5, 0x1ff
	v_med3_i32 v80, v3, v4, v5
	v_lshl_add_u32 v80, v80, 2, s71
	ds_read_b32 v80, v80
	v_add_u32_e32 v81, 0xfffffff0, v3
	v_med3_i32 v81, v81, v4, v5
	v_lshl_add_u32 v81, v81, 2, s71
	ds_read_b32 v81, v81
	v_add_u32_e32 v82, 0xffffffe0, v3
	v_med3_i32 v82, v82, v4, v5
	v_lshl_add_u32 v82, v82, 2, s71
	ds_read_b32 v82, v82
	v_add_u32_e32 v83, 0xffffffd0, v3
	v_med3_i32 v83, v83, v4, v5
	v_lshl_add_u32 v83, v83, 2, s71
	ds_read_b32 v83, v83
	v_add_u32_e32 v84, 0xffffff80, v3
	v_med3_i32 v84, v84, v4, v5
	v_lshl_add_u32 v84, v84, 2, s71
	ds_read_b32 v84, v84
	v_add_u32_e32 v85, 0xffffff70, v3
	v_med3_i32 v85, v85, v4, v5
	v_lshl_add_u32 v85, v85, 2, s71
	ds_read_b32 v85, v85
	v_add_u32_e32 v86, 0xffffff60, v3
	v_med3_i32 v86, v86, v4, v5
	v_lshl_add_u32 v86, v86, 2, s71
	ds_read_b32 v86, v86
	v_add_u32_e32 v87, 0xffffff50, v3
	v_med3_i32 v87, v87, v4, v5
	v_lshl_add_u32 v87, v87, 2, s71
	ds_read_b32 v87, v87
	v_add_u32_e32 v88, 0xffffff00, v3
	v_med3_i32 v88, v88, v4, v5
	v_lshl_add_u32 v88, v88, 2, s71
	ds_read_b32 v88, v88
	v_add_u32_e32 v89, 0xfffffef0, v3
	v_med3_i32 v89, v89, v4, v5
	v_lshl_add_u32 v89, v89, 2, s71
	ds_read_b32 v89, v89
	v_add_u32_e32 v90, 0xfffffee0, v3
	v_med3_i32 v90, v90, v4, v5
	v_lshl_add_u32 v90, v90, 2, s71
	ds_read_b32 v90, v90
	v_add_u32_e32 v91, 0xfffffed0, v3
	v_med3_i32 v91, v91, v4, v5
	v_lshl_add_u32 v91, v91, 2, s71
	ds_read_b32 v91, v91
	v_add_u32_e32 v92, 0xfffffe80, v3
	v_med3_i32 v92, v92, v4, v5
	v_lshl_add_u32 v92, v92, 2, s71
	ds_read_b32 v92, v92
	v_add_u32_e32 v93, 0xfffffe70, v3
	v_med3_i32 v93, v93, v4, v5
	v_lshl_add_u32 v93, v93, 2, s71
	ds_read_b32 v93, v93
	v_add_u32_e32 v94, 0xfffffe60, v3
	v_med3_i32 v94, v94, v4, v5
	v_lshl_add_u32 v94, v94, 2, s71
	ds_read_b32 v94, v94
	v_add_u32_e32 v95, 0xfffffe50, v3
	v_med3_i32 v95, v95, v4, v5
	v_lshl_add_u32 v95, v95, 2, s71
	ds_read_b32 v95, v95
	s_waitcnt lgkmcnt(15)
	v_add_f32_e32 v32, v32, v80
	s_waitcnt lgkmcnt(14)
	v_add_f32_e32 v33, v33, v81
	s_waitcnt lgkmcnt(13)
	v_add_f32_e32 v34, v34, v82
	s_waitcnt lgkmcnt(12)
	v_add_f32_e32 v35, v35, v83
	s_waitcnt lgkmcnt(11)
	v_add_f32_e32 v36, v36, v84
	s_waitcnt lgkmcnt(10)
	v_add_f32_e32 v37, v37, v85
	s_waitcnt lgkmcnt(9)
	v_add_f32_e32 v38, v38, v86
	s_waitcnt lgkmcnt(8)
	v_add_f32_e32 v39, v39, v87
	s_waitcnt lgkmcnt(7)
	v_add_f32_e32 v40, v40, v88
	s_waitcnt lgkmcnt(6)
	v_add_f32_e32 v41, v41, v89
	s_waitcnt lgkmcnt(5)
	v_add_f32_e32 v42, v42, v90
	s_waitcnt lgkmcnt(4)
	v_add_f32_e32 v43, v43, v91
	s_waitcnt lgkmcnt(3)
	v_add_f32_e32 v44, v44, v92
	s_waitcnt lgkmcnt(2)
	v_add_f32_e32 v45, v45, v93
	s_waitcnt lgkmcnt(1)
	v_add_f32_e32 v46, v46, v94
	s_waitcnt lgkmcnt(0)
	v_add_f32_e32 v47, v47, v95

; #define LAS __attribute__((address_space(3)))
; DI f32x16 mfma32(bf16x8 a, bf16x8 b, f32x16 c) { return __builtin_amdgcn_mfma_f32_32x32x16_bf16(a, b, c, 0, 0, 0); }
; DI f32x16 splat16(float v) { f32x16 z; for (int i = 0; i < 16; ++i) z[i] = v; return z; }
; DI void nsa_attn_phase(int wv, LAS unsigned char* lds, const bf16_t* Q, const bf16_t* slab, const bf16_t* VT2, const float* gates, const bf16_t* KCMP, const bf16_t* VCMPT,
;                        const float* rel_bias, bf16_t* O) {
;     ...
;                 for (int t = 0; t < 4; ++t) {
;                     if (t < nsub) {
;                         const bool farc = TW - (16 * (32 * t + 31) + 31) >= 127;
;                         s4[t] = splat16(farc ? c31 : 0.f);
;                         bf16x8 kfc[4];
; #pragma unroll
;                         for (int ks = 0; ks < 4; ++ks) kfc[ks] = *(const LAS bf16x8*)(lds + OFF_KC + (32 * t + r) * KCS + 32 * ks + 16 * hh);
; #pragma unroll
;                         for (int ks = 0; ks < 4; ++ks) s4[t] = mfma32(kfc[ks], qf[ks], s4[t]);
;                         if (!farc) {
;                             const int d0 = tq - 31 - 16 * (32 * t + 4 * hh);
; #pragma unroll
;                             for (int i = 0; i < 16; ++i) {
;                                 const int dist = d0 - 16 * ((i & 3) + 8 * (i >> 2));
;                                 const float bias = mylut[dist < 0 ? 0 : (dist > 127 ? 127 : dist)];
;                                 s4[t][i] = dist >= 0 ? s4[t][i] + bias : NEGF;
;                             }
;                         }
; #pragma unroll
;                         for (int i = 0; i < 16; ++i) mx = fmaxf(mx, s4[t][i]);
;                     }
.LBB0_2348:
	s_cmp_gt_i32 s0, 2
	s_cselect_b64 s[12:13], -1, 0
	s_cmp_lt_i32 s0, 3
	s_cbranch_scc1 .LBB0_2384
	ds_read_b128 v[4:7], v2 offset:13824
	s_cmpk_gt_u32 s90, 0x88d
	s_cselect_b64 vcc, -1, 0
	s_waitcnt lgkmcnt(0)
	v_cndmask_b32_e32 v16, 0, v113, vcc
	v_mov_b32_e32 v17, v16
	v_mov_b32_e32 v18, v16
	v_mov_b32_e32 v19, v16
	v_mov_b32_e32 v20, v16
	v_mov_b32_e32 v21, v16
	v_mov_b32_e32 v22, v16
	v_mov_b32_e32 v23, v16
	v_mov_b32_e32 v24, v16
	v_mov_b32_e32 v25, v16
	v_mov_b32_e32 v26, v16
	v_mov_b32_e32 v27, v16
	v_mov_b32_e32 v28, v16
	v_mov_b32_e32 v29, v16
	v_mov_b32_e32 v30, v16
	v_mov_b32_e32 v31, v16
	s_and_b64 vcc, exec, vcc
	s_waitcnt vmcnt(0)
	v_mfma_f32_32x32x16_bf16 v[16:31], v[4:7], v[176:179], v[16:31]
	ds_read_b128 v[4:7], v2 offset:13856
	s_waitcnt lgkmcnt(0)
	v_mfma_f32_32x32x16_bf16 v[16:31], v[4:7], v[180:183], v[16:31]
	ds_read_b128 v[4:7], v2 offset:13888
	s_waitcnt lgkmcnt(0)
	v_mfma_f32_32x32x16_bf16 v[16:31], v[4:7], v[184:187], v[16:31]
	ds_read_b128 v[2:5], v2 offset:13920
	s_waitcnt lgkmcnt(0)
	v_mfma_f32_32x32x16_bf16 v[16:31], v[2:5], v[188:191], v[16:31]
	s_cbranch_vccnz .LBB0_2383
	s_movk_i32 s0, 0xf9e1
	v_add3_u32 v0, v210, v0, s0
	v_mov_b32_e32 v4, 0xffffffc0
	v_mov_b32_e32 v5, 0x1ff
	v_med3_i32 v80, v0, v4, v5
	v_lshl_add_u32 v80, v80, 2, s71
	ds_read_b32 v80, v80
	v_add_u32_e32 v81, 0xfffffff0, v0
	v_med3_i32 v81, v81, v4, v5
	v_lshl_add_u32 v81, v81, 2, s71
	ds_read_b32 v81, v81
	v_add_u32_e32 v82, 0xffffffe0, v0
	v_med3_i32 v82, v82, v4, v5
	v_lshl_add_u32 v82, v82, 2, s71
	ds_read_b32 v82, v82
	v_add_u32_e32 v83, 0xffffffd0, v0
	v_med3_i32 v83, v83, v4, v5
	v_lshl_add_u32 v83, v83, 2, s71
	ds_read_b32 v83, v83
	v_add_u32_e32 v84, 0xffffff80, v0
	v_med3_i32 v84, v84, v4, v5
	v_lshl_add_u32 v84, v84, 2, s71
	ds_read_b32 v84, v84
	v_add_u32_e32 v85, 0xffffff70, v0
	v_med3_i32 v85, v85, v4, v5
	v_lshl_add_u32 v85, v85, 2, s71
	ds_read_b32 v85, v85
	v_add_u32_e32 v86, 0xffffff60, v0
	v_med3_i32 v86, v86, v4, v5
	v_lshl_add_u32 v86, v86, 2, s71
	ds_read_b32 v86, v86
	v_add_u32_e32 v87, 0xffffff50, v0
	v_med3_i32 v87, v87, v4, v5
	v_lshl_add_u32 v87, v87, 2, s71
	ds_read_b32 v87, v87
	v_add_u32_e32 v88, 0xffffff00, v0
	v_med3_i32 v88, v88, v4, v5
	v_lshl_add_u32 v88, v88, 2, s71
	ds_read_b32 v88, v88
	v_add_u32_e32 v89, 0xfffffef0, v0
	v_med3_i32 v89, v89, v4, v5
	v_lshl_add_u32 v89, v89, 2, s71
	ds_read_b32 v89, v89
	v_add_u32_e32 v90, 0xfffffee0, v0
	v_med3_i32 v90, v90, v4, v5
	v_lshl_add_u32 v90, v90, 2, s71
	ds_read_b32 v90, v90
	v_add_u32_e32 v91, 0xfffffed0, v0
	v_med3_i32 v91, v91, v4, v5
	v_lshl_add_u32 v91, v91, 2, s71
	ds_read_b32 v91, v91
	v_add_u32_e32 v92, 0xfffffe80, v0
	v_med3_i32 v92, v92, v4, v5
	v_lshl_add_u32 v92, v92, 2, s71
	ds_read_b32 v92, v92
	v_add_u32_e32 v93, 0xfffffe70, v0
	v_med3_i32 v93, v93, v4, v5
	v_lshl_add_u32 v93, v93, 2, s71
	ds_read_b32 v93, v93
	v_add_u32_e32 v94, 0xfffffe60, v0
	v_med3_i32 v94, v94, v4, v5
	v_lshl_add_u32 v94, v94, 2, s71
	ds_read_b32 v94, v94
	v_add_u32_e32 v95, 0xfffffe50, v0
	v_med3_i32 v95, v95, v4, v5
	v_lshl_add_u32 v95, v95, 2, s71
	ds_read_b32 v95, v95
	s_waitcnt lgkmcnt(15)
	v_add_f32_e32 v16, v16, v80
	s_waitcnt lgkmcnt(14)
	v_add_f32_e32 v17, v17, v81
	s_waitcnt lgkmcnt(13)
	v_add_f32_e32 v18, v18, v82
	s_waitcnt lgkmcnt(12)
	v_add_f32_e32 v19, v19, v83
	s_waitcnt lgkmcnt(11)
	v_add_f32_e32 v20, v20, v84
	s_waitcnt lgkmcnt(10)
	v_add_f32_e32 v21, v21, v85
	s_waitcnt lgkmcnt(9)
	v_add_f32_e32 v22, v22, v86
	s_waitcnt lgkmcnt(8)
	v_add_f32_e32 v23, v23, v87
	s_waitcnt lgkmcnt(7)
	v_add_f32_e32 v24, v24, v88
	s_waitcnt lgkmcnt(6)
	v_add_f32_e32 v25, v25, v89
	s_waitcnt lgkmcnt(5)
	v_add_f32_e32 v26, v26, v90
	s_waitcnt lgkmcnt(4)
	v_add_f32_e32 v27, v27, v91
	s_waitcnt lgkmcnt(3)
	v_add_f32_e32 v28, v28, v92
	s_waitcnt lgkmcnt(2)
	v_add_f32_e32 v29, v29, v93
	s_waitcnt lgkmcnt(1)
	v_add_f32_e32 v30, v30, v94
	s_waitcnt lgkmcnt(0)
	v_add_f32_e32 v31, v31, v95
